# up-GEMM epilogue packed f32 stages, with -log2(e) folded into the conv weights/bias once per tile (the per-element scaling multiply is gone; 1+t becomes a packed fma)
# baseline (speedup 1.0000x reference)
.LBB0_1016:
	s_mov_b32 s100, 0xbfb8aa3b
	s_mov_b32 s101, 0xbfb8aa3b
	v_mov_b32_e32 v250, 1.0
	v_mov_b32_e32 v251, 1.0
	s_waitcnt vmcnt(0)
	v_pk_mul_f32 v[120:121], v[120:121], s[100:101]
	v_pk_mul_f32 v[122:123], v[122:123], s[100:101]
	v_pk_mul_f32 v[128:129], v[128:129], s[100:101]
	v_pk_mul_f32 v[130:131], v[130:131], s[100:101]
	v_pk_mul_f32 v[136:137], v[136:137], s[100:101]
	v_pk_mul_f32 v[138:139], v[138:139], s[100:101]
	v_pk_mul_f32 v[140:141], v[140:141], s[100:101]
	v_pk_mul_f32 v[142:143], v[142:143], s[100:101]
	v_pk_mul_f32 v[144:145], v[144:145], s[100:101]
	v_pk_mul_f32 v[146:147], v[146:147], s[100:101]
	v_pk_mul_f32 v[148:149], v[148:149], s[100:101]
	v_pk_mul_f32 v[150:151], v[150:151], s[100:101]
	v_pk_mul_f32 v[152:153], v[152:153], s[100:101]
	v_pk_mul_f32 v[154:155], v[154:155], s[100:101]
	v_pk_mul_f32 v[156:157], v[156:157], s[100:101]
	v_pk_mul_f32 v[158:159], v[158:159], s[100:101]
	v_pk_fma_f32 v[200:201], v[108:109], v[156:157], v[128:129]
	s_waitcnt lgkmcnt(4)
	s_nop 1
	v_fmac_f32_dpp v200, v108, v148 row_shr:1 row_mask:0xf bank_mask:0xf
	v_fmac_f32_dpp v200, v192, v148 row_shl:15 row_mask:0xf bank_mask:0xf
	v_fmac_f32_dpp v200, v108, v152 row_shl:1 row_mask:0xf bank_mask:0xf
	v_fmac_f32_dpp v200, v112, v152 row_shr:15 row_mask:0xf bank_mask:0xf
	v_fmac_f32_dpp v201, v109, v149 row_shr:1 row_mask:0xf bank_mask:0xf
	v_fmac_f32_dpp v201, v193, v149 row_shl:15 row_mask:0xf bank_mask:0xf
	v_fmac_f32_dpp v201, v109, v153 row_shl:1 row_mask:0xf bank_mask:0xf
	v_fmac_f32_dpp v201, v113, v153 row_shr:15 row_mask:0xf bank_mask:0xf
	v_pk_fma_f32 v[202:203], v[110:111], v[158:159], v[130:131]
	v_fmac_f32_dpp v202, v110, v150 row_shr:1 row_mask:0xf bank_mask:0xf
	v_fmac_f32_dpp v202, v194, v150 row_shl:15 row_mask:0xf bank_mask:0xf
	v_fmac_f32_dpp v202, v110, v154 row_shl:1 row_mask:0xf bank_mask:0xf
	v_fmac_f32_dpp v202, v114, v154 row_shr:15 row_mask:0xf bank_mask:0xf
	v_fmac_f32_dpp v203, v111, v151 row_shr:1 row_mask:0xf bank_mask:0xf
	v_fmac_f32_dpp v203, v195, v151 row_shl:15 row_mask:0xf bank_mask:0xf
	v_fmac_f32_dpp v203, v111, v155 row_shl:1 row_mask:0xf bank_mask:0xf
	v_fmac_f32_dpp v203, v115, v155 row_shr:15 row_mask:0xf bank_mask:0xf
	v_pk_fma_f32 v[204:205], v[104:105], v[144:145], v[120:121]
	s_waitcnt lgkmcnt(3)
	v_fmac_f32_dpp v204, v104, v136 row_shr:1 row_mask:0xf bank_mask:0xf
	v_fmac_f32_dpp v204, v188, v136 row_shl:15 row_mask:0xf bank_mask:0xf
	v_fmac_f32_dpp v204, v104, v140 row_shl:1 row_mask:0xf bank_mask:0xf
	v_fmac_f32_dpp v204, v100, v140 row_shr:15 row_mask:0xf bank_mask:0xf
	v_fmac_f32_dpp v205, v105, v137 row_shr:1 row_mask:0xf bank_mask:0xf
	v_fmac_f32_dpp v205, v189, v137 row_shl:15 row_mask:0xf bank_mask:0xf
	v_fmac_f32_dpp v205, v105, v141 row_shl:1 row_mask:0xf bank_mask:0xf
	v_fmac_f32_dpp v205, v101, v141 row_shr:15 row_mask:0xf bank_mask:0xf
	v_pk_fma_f32 v[206:207], v[106:107], v[146:147], v[122:123]
	v_fmac_f32_dpp v206, v106, v138 row_shr:1 row_mask:0xf bank_mask:0xf
	v_fmac_f32_dpp v206, v190, v138 row_shl:15 row_mask:0xf bank_mask:0xf
	v_fmac_f32_dpp v206, v106, v142 row_shl:1 row_mask:0xf bank_mask:0xf
	v_fmac_f32_dpp v206, v102, v142 row_shr:15 row_mask:0xf bank_mask:0xf
	v_fmac_f32_dpp v207, v107, v139 row_shr:1 row_mask:0xf bank_mask:0xf
	v_fmac_f32_dpp v207, v191, v139 row_shl:15 row_mask:0xf bank_mask:0xf
	v_fmac_f32_dpp v207, v107, v143 row_shl:1 row_mask:0xf bank_mask:0xf
	v_fmac_f32_dpp v207, v103, v143 row_shr:15 row_mask:0xf bank_mask:0xf
	v_exp_f32_e32 v246, v200
	v_exp_f32_e32 v247, v201
	v_exp_f32_e32 v248, v202
	v_exp_f32_e32 v249, v203
	v_exp_f32_e32 v224, v204
	v_exp_f32_e32 v225, v205
	v_exp_f32_e32 v228, v206
	v_exp_f32_e32 v229, v207
	v_pk_fma_f32 v[246:247], v[246:247], s[100:101], s[100:101]
	v_pk_fma_f32 v[248:249], v[248:249], s[100:101], s[100:101]
	v_pk_fma_f32 v[224:225], v[224:225], s[100:101], s[100:101]
	v_pk_fma_f32 v[228:229], v[228:229], s[100:101], s[100:101]
	v_rcp_f32_e32 v246, v246
	v_rcp_f32_e32 v247, v247
	v_rcp_f32_e32 v248, v248
	v_rcp_f32_e32 v249, v249
	v_rcp_f32_e32 v224, v224
	v_rcp_f32_e32 v225, v225
	v_rcp_f32_e32 v228, v228
	v_rcp_f32_e32 v229, v229
	s_nop 0
	v_pk_mul_f32 v[246:247], v[200:201], v[246:247]
	v_pk_mul_f32 v[248:249], v[202:203], v[248:249]
	v_pk_mul_f32 v[224:225], v[204:205], v[224:225]
	v_pk_mul_f32 v[228:229], v[206:207], v[228:229]
	v_pk_mul_f32 v[246:247], v[160:161], v[246:247]
	v_pk_mul_f32 v[248:249], v[162:163], v[248:249]
	v_pk_mul_f32 v[224:225], v[132:133], v[224:225]
	v_pk_mul_f32 v[228:229], v[134:135], v[228:229]
	v_lshl_add_u32 v240, s36, 8, v232
	v_cvt_pk_bf16_f32 v160, v246, v247
	v_cvt_pk_bf16_f32 v161, v248, v249
	v_cvt_pk_bf16_f32 v162, v224, v225
	v_mov_b64_e32 v[132:133], s[54:55]
	v_cvt_pk_bf16_f32 v163, v228, v229
	v_mad_i64_i32 v[188:189], s[4:5], v240, s79, v[132:133]
	v_lshlrev_b64 v[134:135], 1, v[222:223]
	v_lshl_add_u64 v[188:189], v[188:189], 0, v[134:135]
	global_store_dwordx4 v[188:189], v[160:163], off
	s_andn2_b64 vcc, exec, s[44:45]
	s_nop 0
	v_pk_fma_f32 v[200:201], v[112:113], v[156:157], v[128:129]
	v_fmac_f32_dpp v200, v112, v148 row_shr:1 row_mask:0xf bank_mask:0xf
	v_fmac_f32_dpp v200, v108, v148 row_shl:15 row_mask:0xf bank_mask:0xf
	v_fmac_f32_dpp v200, v112, v152 row_shl:1 row_mask:0xf bank_mask:0xf
	v_fmac_f32_dpp v200, v86, v152 row_shr:15 row_mask:0xf bank_mask:0xf
	v_fmac_f32_dpp v201, v113, v149 row_shr:1 row_mask:0xf bank_mask:0xf
	v_fmac_f32_dpp v201, v109, v149 row_shl:15 row_mask:0xf bank_mask:0xf
	v_fmac_f32_dpp v201, v113, v153 row_shl:1 row_mask:0xf bank_mask:0xf
	v_fmac_f32_dpp v201, v87, v153 row_shr:15 row_mask:0xf bank_mask:0xf
	v_pk_fma_f32 v[202:203], v[114:115], v[158:159], v[130:131]
	v_fmac_f32_dpp v202, v114, v150 row_shr:1 row_mask:0xf bank_mask:0xf
	v_fmac_f32_dpp v202, v110, v150 row_shl:15 row_mask:0xf bank_mask:0xf
	v_fmac_f32_dpp v202, v114, v154 row_shl:1 row_mask:0xf bank_mask:0xf
	v_fmac_f32_dpp v202, v88, v154 row_shr:15 row_mask:0xf bank_mask:0xf
	v_fmac_f32_dpp v203, v115, v151 row_shr:1 row_mask:0xf bank_mask:0xf
	v_fmac_f32_dpp v203, v111, v151 row_shl:15 row_mask:0xf bank_mask:0xf
	v_fmac_f32_dpp v203, v115, v155 row_shl:1 row_mask:0xf bank_mask:0xf
	v_fmac_f32_dpp v203, v89, v155 row_shr:15 row_mask:0xf bank_mask:0xf
	v_pk_fma_f32 v[204:205], v[100:101], v[144:145], v[120:121]
	v_fmac_f32_dpp v204, v100, v136 row_shr:1 row_mask:0xf bank_mask:0xf
	v_fmac_f32_dpp v204, v104, v136 row_shl:15 row_mask:0xf bank_mask:0xf
	v_fmac_f32_dpp v204, v100, v140 row_shl:1 row_mask:0xf bank_mask:0xf
	v_fmac_f32_dpp v204, v82, v140 row_shr:15 row_mask:0xf bank_mask:0xf
	v_fmac_f32_dpp v205, v101, v137 row_shr:1 row_mask:0xf bank_mask:0xf
	v_fmac_f32_dpp v205, v105, v137 row_shl:15 row_mask:0xf bank_mask:0xf
	v_fmac_f32_dpp v205, v101, v141 row_shl:1 row_mask:0xf bank_mask:0xf
	v_fmac_f32_dpp v205, v83, v141 row_shr:15 row_mask:0xf bank_mask:0xf
	v_pk_fma_f32 v[206:207], v[102:103], v[146:147], v[122:123]
	v_fmac_f32_dpp v206, v102, v138 row_shr:1 row_mask:0xf bank_mask:0xf
	v_fmac_f32_dpp v206, v106, v138 row_shl:15 row_mask:0xf bank_mask:0xf
	v_fmac_f32_dpp v206, v102, v142 row_shl:1 row_mask:0xf bank_mask:0xf
	v_fmac_f32_dpp v206, v84, v142 row_shr:15 row_mask:0xf bank_mask:0xf
	v_fmac_f32_dpp v207, v103, v139 row_shr:1 row_mask:0xf bank_mask:0xf
	v_fmac_f32_dpp v207, v107, v139 row_shl:15 row_mask:0xf bank_mask:0xf
	v_fmac_f32_dpp v207, v103, v143 row_shl:1 row_mask:0xf bank_mask:0xf
	v_fmac_f32_dpp v207, v85, v143 row_shr:15 row_mask:0xf bank_mask:0xf
	v_exp_f32_e32 v246, v200
	v_exp_f32_e32 v247, v201
	v_exp_f32_e32 v248, v202
	v_exp_f32_e32 v249, v203
	v_exp_f32_e32 v224, v204
	v_exp_f32_e32 v225, v205
	v_exp_f32_e32 v228, v206
	v_exp_f32_e32 v229, v207
	v_pk_fma_f32 v[246:247], v[246:247], s[100:101], s[100:101]
	v_pk_fma_f32 v[248:249], v[248:249], s[100:101], s[100:101]
	v_pk_fma_f32 v[224:225], v[224:225], s[100:101], s[100:101]
	v_pk_fma_f32 v[228:229], v[228:229], s[100:101], s[100:101]
	v_rcp_f32_e32 v246, v246
	v_rcp_f32_e32 v247, v247
	v_rcp_f32_e32 v248, v248
	v_rcp_f32_e32 v249, v249
	v_rcp_f32_e32 v224, v224
	v_rcp_f32_e32 v225, v225
	v_rcp_f32_e32 v228, v228
	v_rcp_f32_e32 v229, v229
	s_nop 0
	v_pk_mul_f32 v[246:247], v[200:201], v[246:247]
	v_pk_mul_f32 v[248:249], v[202:203], v[248:249]
	v_pk_mul_f32 v[224:225], v[204:205], v[224:225]
	v_pk_mul_f32 v[228:229], v[206:207], v[228:229]
	v_pk_mul_f32 v[246:247], v[124:125], v[246:247]
	v_pk_mul_f32 v[248:249], v[126:127], v[248:249]
	v_pk_mul_f32 v[224:225], v[116:117], v[224:225]
	v_pk_mul_f32 v[228:229], v[118:119], v[228:229]
	v_cvt_pk_bf16_f32 v104, v246, v247
	v_or_b32_e32 v108, 16, v240
	v_cvt_pk_bf16_f32 v105, v248, v249
	v_mad_i64_i32 v[108:109], s[4:5], v108, s79, v[132:133]
	v_lshl_add_u64 v[108:109], v[108:109], 0, v[134:135]
	v_cvt_pk_bf16_f32 v106, v224, v225
	v_cvt_pk_bf16_f32 v107, v228, v229
	global_store_dwordx4 v[108:109], v[104:107], off
	v_pk_fma_f32 v[204:205], v[82:83], v[144:145], v[120:121]
	v_fmac_f32_dpp v204, v82, v136 row_shr:1 row_mask:0xf bank_mask:0xf
	v_fmac_f32_dpp v204, v100, v136 row_shl:15 row_mask:0xf bank_mask:0xf
	v_fmac_f32_dpp v204, v82, v140 row_shl:1 row_mask:0xf bank_mask:0xf
	v_fmac_f32_dpp v204, v66, v140 row_shr:15 row_mask:0xf bank_mask:0xf
	v_fmac_f32_dpp v205, v83, v137 row_shr:1 row_mask:0xf bank_mask:0xf
	v_fmac_f32_dpp v205, v101, v137 row_shl:15 row_mask:0xf bank_mask:0xf
	v_fmac_f32_dpp v205, v83, v141 row_shl:1 row_mask:0xf bank_mask:0xf
	v_fmac_f32_dpp v205, v67, v141 row_shr:15 row_mask:0xf bank_mask:0xf
	v_pk_fma_f32 v[206:207], v[84:85], v[146:147], v[122:123]
	v_pk_fma_f32 v[200:201], v[86:87], v[156:157], v[128:129]
	v_fmac_f32_dpp v206, v84, v138 row_shr:1 row_mask:0xf bank_mask:0xf
	v_fmac_f32_dpp v206, v102, v138 row_shl:15 row_mask:0xf bank_mask:0xf
	v_fmac_f32_dpp v206, v84, v142 row_shl:1 row_mask:0xf bank_mask:0xf
	v_fmac_f32_dpp v206, v68, v142 row_shr:15 row_mask:0xf bank_mask:0xf
	v_fmac_f32_dpp v200, v86, v148 row_shr:1 row_mask:0xf bank_mask:0xf
	v_fmac_f32_dpp v200, v112, v148 row_shl:15 row_mask:0xf bank_mask:0xf
	v_fmac_f32_dpp v200, v86, v152 row_shl:1 row_mask:0xf bank_mask:0xf
	v_fmac_f32_dpp v200, v74, v152 row_shr:15 row_mask:0xf bank_mask:0xf
	v_fmac_f32_dpp v207, v85, v139 row_shr:1 row_mask:0xf bank_mask:0xf
	v_fmac_f32_dpp v207, v103, v139 row_shl:15 row_mask:0xf bank_mask:0xf
	v_fmac_f32_dpp v207, v85, v143 row_shl:1 row_mask:0xf bank_mask:0xf
	v_fmac_f32_dpp v207, v69, v143 row_shr:15 row_mask:0xf bank_mask:0xf
	v_fmac_f32_dpp v201, v87, v149 row_shr:1 row_mask:0xf bank_mask:0xf
	v_fmac_f32_dpp v201, v113, v149 row_shl:15 row_mask:0xf bank_mask:0xf
	v_fmac_f32_dpp v201, v87, v153 row_shl:1 row_mask:0xf bank_mask:0xf
	v_fmac_f32_dpp v201, v75, v153 row_shr:15 row_mask:0xf bank_mask:0xf
	v_pk_fma_f32 v[202:203], v[88:89], v[158:159], v[130:131]
	v_fmac_f32_dpp v202, v88, v150 row_shr:1 row_mask:0xf bank_mask:0xf
	v_fmac_f32_dpp v202, v114, v150 row_shl:15 row_mask:0xf bank_mask:0xf
	v_fmac_f32_dpp v202, v88, v154 row_shl:1 row_mask:0xf bank_mask:0xf
	v_fmac_f32_dpp v202, v76, v154 row_shr:15 row_mask:0xf bank_mask:0xf
	v_fmac_f32_dpp v203, v89, v151 row_shr:1 row_mask:0xf bank_mask:0xf
	v_fmac_f32_dpp v203, v115, v151 row_shl:15 row_mask:0xf bank_mask:0xf
	v_fmac_f32_dpp v203, v89, v155 row_shl:1 row_mask:0xf bank_mask:0xf
	v_fmac_f32_dpp v203, v77, v155 row_shr:15 row_mask:0xf bank_mask:0xf
	v_exp_f32_e32 v246, v200
	v_exp_f32_e32 v247, v201
	v_exp_f32_e32 v248, v202
	v_exp_f32_e32 v249, v203
	v_exp_f32_e32 v224, v204
	v_exp_f32_e32 v225, v205
	v_exp_f32_e32 v228, v206
	v_exp_f32_e32 v229, v207
	v_pk_fma_f32 v[246:247], v[246:247], s[100:101], s[100:101]
	v_pk_fma_f32 v[248:249], v[248:249], s[100:101], s[100:101]
	v_pk_fma_f32 v[224:225], v[224:225], s[100:101], s[100:101]
	v_pk_fma_f32 v[228:229], v[228:229], s[100:101], s[100:101]
	v_rcp_f32_e32 v246, v246
	v_rcp_f32_e32 v247, v247
	v_rcp_f32_e32 v248, v248
	v_rcp_f32_e32 v249, v249
	v_rcp_f32_e32 v224, v224
	v_rcp_f32_e32 v225, v225
	v_rcp_f32_e32 v228, v228
	v_rcp_f32_e32 v229, v229
	s_nop 0
	v_pk_mul_f32 v[246:247], v[200:201], v[246:247]
	v_pk_mul_f32 v[248:249], v[202:203], v[248:249]
	v_pk_mul_f32 v[224:225], v[204:205], v[224:225]
	v_pk_mul_f32 v[228:229], v[206:207], v[228:229]
	v_pk_mul_f32 v[246:247], v[94:95], v[246:247]
	v_pk_mul_f32 v[248:249], v[96:97], v[248:249]
	v_pk_mul_f32 v[224:225], v[90:91], v[224:225]
	v_pk_mul_f32 v[228:229], v[92:93], v[228:229]
	v_cvt_pk_bf16_f32 v90, v246, v247
	v_or_b32_e32 v94, 32, v240
	v_mad_i64_i32 v[94:95], s[4:5], v94, s79, v[132:133]
	v_lshl_add_u64 v[94:95], v[94:95], 0, v[134:135]
	v_cvt_pk_bf16_f32 v91, v248, v249
	v_cvt_pk_bf16_f32 v92, v224, v225
	v_cvt_pk_bf16_f32 v93, v228, v229
	global_store_dwordx4 v[94:95], v[90:93], off
	s_nop 1
	v_pk_fma_f32 v[200:201], v[74:75], v[156:157], v[128:129]
	s_nop 1
	v_fmac_f32_dpp v200, v74, v148 row_shr:1 row_mask:0xf bank_mask:0xf
	v_fmac_f32_dpp v200, v86, v148 row_shl:15 row_mask:0xf bank_mask:0xf
	v_fmac_f32_dpp v200, v74, v152 row_shl:1 row_mask:0xf bank_mask:0xf
	v_fmac_f32_dpp v200, v184, v152 row_shr:15 row_mask:0xf bank_mask:0xf
	v_fmac_f32_dpp v201, v75, v149 row_shr:1 row_mask:0xf bank_mask:0xf
	v_fmac_f32_dpp v201, v87, v149 row_shl:15 row_mask:0xf bank_mask:0xf
	v_fmac_f32_dpp v201, v75, v153 row_shl:1 row_mask:0xf bank_mask:0xf
	v_fmac_f32_dpp v201, v185, v153 row_shr:15 row_mask:0xf bank_mask:0xf
	v_pk_fma_f32 v[202:203], v[76:77], v[158:159], v[130:131]
	v_fmac_f32_dpp v202, v76, v150 row_shr:1 row_mask:0xf bank_mask:0xf
	v_fmac_f32_dpp v202, v88, v150 row_shl:15 row_mask:0xf bank_mask:0xf
	v_fmac_f32_dpp v202, v76, v154 row_shl:1 row_mask:0xf bank_mask:0xf
	v_fmac_f32_dpp v202, v186, v154 row_shr:15 row_mask:0xf bank_mask:0xf
	v_fmac_f32_dpp v203, v77, v151 row_shr:1 row_mask:0xf bank_mask:0xf
	v_fmac_f32_dpp v203, v89, v151 row_shl:15 row_mask:0xf bank_mask:0xf
	v_fmac_f32_dpp v203, v77, v155 row_shl:1 row_mask:0xf bank_mask:0xf
	v_fmac_f32_dpp v203, v187, v155 row_shr:15 row_mask:0xf bank_mask:0xf
	v_pk_fma_f32 v[204:205], v[66:67], v[144:145], v[120:121]
	s_waitcnt lgkmcnt(2)
	v_fmac_f32_dpp v204, v66, v136 row_shr:1 row_mask:0xf bank_mask:0xf
	v_fmac_f32_dpp v204, v82, v136 row_shl:15 row_mask:0xf bank_mask:0xf
	v_fmac_f32_dpp v204, v66, v140 row_shl:1 row_mask:0xf bank_mask:0xf
	v_fmac_f32_dpp v204, v180, v140 row_shr:15 row_mask:0xf bank_mask:0xf
	v_fmac_f32_dpp v205, v67, v137 row_shr:1 row_mask:0xf bank_mask:0xf
	v_fmac_f32_dpp v205, v83, v137 row_shl:15 row_mask:0xf bank_mask:0xf
	v_fmac_f32_dpp v205, v67, v141 row_shl:1 row_mask:0xf bank_mask:0xf
	v_fmac_f32_dpp v205, v181, v141 row_shr:15 row_mask:0xf bank_mask:0xf
	v_pk_fma_f32 v[206:207], v[68:69], v[146:147], v[122:123]
	v_fmac_f32_dpp v206, v68, v138 row_shr:1 row_mask:0xf bank_mask:0xf
	v_fmac_f32_dpp v206, v84, v138 row_shl:15 row_mask:0xf bank_mask:0xf
	v_fmac_f32_dpp v206, v68, v142 row_shl:1 row_mask:0xf bank_mask:0xf
	v_fmac_f32_dpp v206, v182, v142 row_shr:15 row_mask:0xf bank_mask:0xf
	v_fmac_f32_dpp v207, v69, v139 row_shr:1 row_mask:0xf bank_mask:0xf
	v_fmac_f32_dpp v207, v85, v139 row_shl:15 row_mask:0xf bank_mask:0xf
	v_fmac_f32_dpp v207, v69, v143 row_shl:1 row_mask:0xf bank_mask:0xf
	v_fmac_f32_dpp v207, v183, v143 row_shr:15 row_mask:0xf bank_mask:0xf
	v_exp_f32_e32 v246, v200
	v_exp_f32_e32 v247, v201
	v_exp_f32_e32 v248, v202
	v_exp_f32_e32 v249, v203
	v_exp_f32_e32 v224, v204
	v_exp_f32_e32 v225, v205
	v_exp_f32_e32 v228, v206
	v_exp_f32_e32 v229, v207
	v_pk_fma_f32 v[246:247], v[246:247], s[100:101], s[100:101]
	v_pk_fma_f32 v[248:249], v[248:249], s[100:101], s[100:101]
	v_pk_fma_f32 v[224:225], v[224:225], s[100:101], s[100:101]
	v_pk_fma_f32 v[228:229], v[228:229], s[100:101], s[100:101]
	v_rcp_f32_e32 v246, v246
	v_rcp_f32_e32 v247, v247
	v_rcp_f32_e32 v248, v248
	v_rcp_f32_e32 v249, v249
	v_rcp_f32_e32 v224, v224
	v_rcp_f32_e32 v225, v225
	v_rcp_f32_e32 v228, v228
	v_rcp_f32_e32 v229, v229
	s_nop 0
	v_pk_mul_f32 v[246:247], v[200:201], v[246:247]
	v_pk_mul_f32 v[248:249], v[202:203], v[248:249]
	v_pk_mul_f32 v[224:225], v[204:205], v[224:225]
	v_pk_mul_f32 v[228:229], v[206:207], v[228:229]
	v_pk_mul_f32 v[246:247], v[78:79], v[246:247]
	v_pk_mul_f32 v[248:249], v[80:81], v[248:249]
	v_pk_mul_f32 v[224:225], v[70:71], v[224:225]
	v_pk_mul_f32 v[228:229], v[72:73], v[228:229]
	v_cvt_pk_bf16_f32 v66, v246, v247
	v_cvt_pk_bf16_f32 v67, v248, v249
	v_cvt_pk_bf16_f32 v68, v224, v225
	v_or_b32_e32 v70, 48, v240
	v_mad_i64_i32 v[70:71], s[4:5], v70, s79, v[132:133]
	v_lshl_add_u64 v[70:71], v[70:71], 0, v[134:135]
	v_cvt_pk_bf16_f32 v69, v228, v229
	global_store_dwordx4 v[70:71], v[66:69], off
	v_pk_fma_f32 v[202:203], v[56:57], v[158:159], v[130:131]
	s_waitcnt lgkmcnt(1)
	v_fmac_f32_dpp v203, v57, v151 row_shr:1 row_mask:0xf bank_mask:0xf
	v_fmac_f32_dpp v203, v179, v151 row_shl:15 row_mask:0xf bank_mask:0xf
	v_fmac_f32_dpp v203, v57, v155 row_shl:1 row_mask:0xf bank_mask:0xf
	v_fmac_f32_dpp v203, v41, v155 row_shr:15 row_mask:0xf bank_mask:0xf
	v_pk_fma_f32 v[204:205], v[50:51], v[144:145], v[120:121]
	v_pk_fma_f32 v[200:201], v[54:55], v[156:157], v[128:129]
	s_nop 1
	v_fmac_f32_dpp v200, v54, v148 row_shr:1 row_mask:0xf bank_mask:0xf
	v_fmac_f32_dpp v200, v176, v148 row_shl:15 row_mask:0xf bank_mask:0xf
	v_fmac_f32_dpp v200, v54, v152 row_shl:1 row_mask:0xf bank_mask:0xf
	v_fmac_f32_dpp v200, v38, v152 row_shr:15 row_mask:0xf bank_mask:0xf
	v_fmac_f32_dpp v201, v55, v149 row_shr:1 row_mask:0xf bank_mask:0xf
	v_fmac_f32_dpp v201, v177, v149 row_shl:15 row_mask:0xf bank_mask:0xf
	v_fmac_f32_dpp v201, v55, v153 row_shl:1 row_mask:0xf bank_mask:0xf
	v_fmac_f32_dpp v201, v39, v153 row_shr:15 row_mask:0xf bank_mask:0xf
	v_fmac_f32_dpp v202, v56, v150 row_shr:1 row_mask:0xf bank_mask:0xf
	v_fmac_f32_dpp v202, v178, v150 row_shl:15 row_mask:0xf bank_mask:0xf
	v_fmac_f32_dpp v202, v56, v154 row_shl:1 row_mask:0xf bank_mask:0xf
	v_fmac_f32_dpp v202, v40, v154 row_shr:15 row_mask:0xf bank_mask:0xf
	s_waitcnt lgkmcnt(0)
	v_fmac_f32_dpp v204, v50, v136 row_shr:1 row_mask:0xf bank_mask:0xf
	v_fmac_f32_dpp v204, v172, v136 row_shl:15 row_mask:0xf bank_mask:0xf
	v_fmac_f32_dpp v204, v50, v140 row_shl:1 row_mask:0xf bank_mask:0xf
	v_fmac_f32_dpp v204, v34, v140 row_shr:15 row_mask:0xf bank_mask:0xf
	v_fmac_f32_dpp v205, v51, v137 row_shr:1 row_mask:0xf bank_mask:0xf
	v_fmac_f32_dpp v205, v173, v137 row_shl:15 row_mask:0xf bank_mask:0xf
	v_fmac_f32_dpp v205, v51, v141 row_shl:1 row_mask:0xf bank_mask:0xf
	v_fmac_f32_dpp v205, v35, v141 row_shr:15 row_mask:0xf bank_mask:0xf
	v_pk_fma_f32 v[206:207], v[52:53], v[146:147], v[122:123]
	v_fmac_f32_dpp v206, v52, v138 row_shr:1 row_mask:0xf bank_mask:0xf
	v_fmac_f32_dpp v206, v174, v138 row_shl:15 row_mask:0xf bank_mask:0xf
	v_fmac_f32_dpp v206, v52, v142 row_shl:1 row_mask:0xf bank_mask:0xf
	v_fmac_f32_dpp v206, v36, v142 row_shr:15 row_mask:0xf bank_mask:0xf
	v_fmac_f32_dpp v207, v53, v139 row_shr:1 row_mask:0xf bank_mask:0xf
	v_fmac_f32_dpp v207, v175, v139 row_shl:15 row_mask:0xf bank_mask:0xf
	v_fmac_f32_dpp v207, v53, v143 row_shl:1 row_mask:0xf bank_mask:0xf
	v_fmac_f32_dpp v207, v37, v143 row_shr:15 row_mask:0xf bank_mask:0xf
	v_exp_f32_e32 v246, v200
	v_exp_f32_e32 v247, v201
	v_exp_f32_e32 v248, v202
	v_exp_f32_e32 v249, v203
	v_exp_f32_e32 v224, v204
	v_exp_f32_e32 v225, v205
	v_exp_f32_e32 v228, v206
	v_exp_f32_e32 v229, v207
	v_pk_fma_f32 v[246:247], v[246:247], s[100:101], s[100:101]
	v_pk_fma_f32 v[248:249], v[248:249], s[100:101], s[100:101]
	v_pk_fma_f32 v[224:225], v[224:225], s[100:101], s[100:101]
	v_pk_fma_f32 v[228:229], v[228:229], s[100:101], s[100:101]
	v_rcp_f32_e32 v246, v246
	v_rcp_f32_e32 v247, v247
	v_rcp_f32_e32 v248, v248
	v_rcp_f32_e32 v249, v249
	v_rcp_f32_e32 v224, v224
	v_rcp_f32_e32 v225, v225
	v_rcp_f32_e32 v228, v228
	v_rcp_f32_e32 v229, v229
	s_nop 0
	v_pk_mul_f32 v[246:247], v[200:201], v[246:247]
	v_pk_mul_f32 v[248:249], v[202:203], v[248:249]
	v_pk_mul_f32 v[224:225], v[204:205], v[224:225]
	v_pk_mul_f32 v[228:229], v[206:207], v[228:229]
	v_pk_mul_f32 v[246:247], v[62:63], v[246:247]
	v_pk_mul_f32 v[248:249], v[64:65], v[248:249]
	v_pk_mul_f32 v[224:225], v[58:59], v[224:225]
	v_pk_mul_f32 v[228:229], v[60:61], v[228:229]
	v_add_u32_e32 v66, 0x80, v240
	v_cvt_pk_bf16_f32 v58, v246, v247
	v_mad_i64_i32 v[62:63], s[4:5], v66, s79, v[132:133]
	v_lshl_add_u64 v[62:63], v[62:63], 0, v[134:135]
	v_cvt_pk_bf16_f32 v59, v248, v249
	v_cvt_pk_bf16_f32 v60, v224, v225
	v_cvt_pk_bf16_f32 v61, v228, v229
	global_store_dwordx4 v[62:63], v[58:61], off
	s_nop 1
	v_pk_fma_f32 v[200:201], v[38:39], v[156:157], v[128:129]
	v_fmac_f32_dpp v200, v38, v148 row_shr:1 row_mask:0xf bank_mask:0xf
	v_fmac_f32_dpp v200, v54, v148 row_shl:15 row_mask:0xf bank_mask:0xf
	v_fmac_f32_dpp v200, v38, v152 row_shl:1 row_mask:0xf bank_mask:0xf
	v_fmac_f32_dpp v200, v22, v152 row_shr:15 row_mask:0xf bank_mask:0xf
	v_fmac_f32_dpp v201, v39, v149 row_shr:1 row_mask:0xf bank_mask:0xf
	v_fmac_f32_dpp v201, v55, v149 row_shl:15 row_mask:0xf bank_mask:0xf
	v_fmac_f32_dpp v201, v39, v153 row_shl:1 row_mask:0xf bank_mask:0xf
	v_fmac_f32_dpp v201, v23, v153 row_shr:15 row_mask:0xf bank_mask:0xf
	v_pk_fma_f32 v[202:203], v[40:41], v[158:159], v[130:131]
	v_fmac_f32_dpp v202, v40, v150 row_shr:1 row_mask:0xf bank_mask:0xf
	v_fmac_f32_dpp v202, v56, v150 row_shl:15 row_mask:0xf bank_mask:0xf
	v_fmac_f32_dpp v202, v40, v154 row_shl:1 row_mask:0xf bank_mask:0xf
	v_fmac_f32_dpp v202, v24, v154 row_shr:15 row_mask:0xf bank_mask:0xf
	v_fmac_f32_dpp v203, v41, v151 row_shr:1 row_mask:0xf bank_mask:0xf
	v_fmac_f32_dpp v203, v57, v151 row_shl:15 row_mask:0xf bank_mask:0xf
	v_fmac_f32_dpp v203, v41, v155 row_shl:1 row_mask:0xf bank_mask:0xf
	v_fmac_f32_dpp v203, v25, v155 row_shr:15 row_mask:0xf bank_mask:0xf
	v_pk_fma_f32 v[204:205], v[34:35], v[144:145], v[120:121]
	v_fmac_f32_dpp v204, v34, v136 row_shr:1 row_mask:0xf bank_mask:0xf
	v_fmac_f32_dpp v204, v50, v136 row_shl:15 row_mask:0xf bank_mask:0xf
	v_fmac_f32_dpp v204, v34, v140 row_shl:1 row_mask:0xf bank_mask:0xf
	v_fmac_f32_dpp v204, v18, v140 row_shr:15 row_mask:0xf bank_mask:0xf
	v_fmac_f32_dpp v205, v35, v137 row_shr:1 row_mask:0xf bank_mask:0xf
	v_fmac_f32_dpp v205, v51, v137 row_shl:15 row_mask:0xf bank_mask:0xf
	v_fmac_f32_dpp v205, v35, v141 row_shl:1 row_mask:0xf bank_mask:0xf
	v_fmac_f32_dpp v205, v19, v141 row_shr:15 row_mask:0xf bank_mask:0xf
	v_pk_fma_f32 v[206:207], v[36:37], v[146:147], v[122:123]
	v_fmac_f32_dpp v206, v36, v138 row_shr:1 row_mask:0xf bank_mask:0xf
	v_fmac_f32_dpp v206, v52, v138 row_shl:15 row_mask:0xf bank_mask:0xf
	v_fmac_f32_dpp v206, v36, v142 row_shl:1 row_mask:0xf bank_mask:0xf
	v_fmac_f32_dpp v206, v20, v142 row_shr:15 row_mask:0xf bank_mask:0xf
	v_fmac_f32_dpp v207, v37, v139 row_shr:1 row_mask:0xf bank_mask:0xf
	v_fmac_f32_dpp v207, v53, v139 row_shl:15 row_mask:0xf bank_mask:0xf
	v_fmac_f32_dpp v207, v37, v143 row_shl:1 row_mask:0xf bank_mask:0xf
	v_fmac_f32_dpp v207, v21, v143 row_shr:15 row_mask:0xf bank_mask:0xf
	v_exp_f32_e32 v246, v200
	v_exp_f32_e32 v247, v201
	v_exp_f32_e32 v248, v202
	v_exp_f32_e32 v249, v203
	v_exp_f32_e32 v224, v204
	v_exp_f32_e32 v225, v205
	v_exp_f32_e32 v228, v206
	v_exp_f32_e32 v229, v207
	v_pk_fma_f32 v[246:247], v[246:247], s[100:101], s[100:101]
	v_pk_fma_f32 v[248:249], v[248:249], s[100:101], s[100:101]
	v_pk_fma_f32 v[224:225], v[224:225], s[100:101], s[100:101]
	v_pk_fma_f32 v[228:229], v[228:229], s[100:101], s[100:101]
	v_rcp_f32_e32 v246, v246
	v_rcp_f32_e32 v247, v247
	v_rcp_f32_e32 v248, v248
	v_rcp_f32_e32 v249, v249
	v_rcp_f32_e32 v224, v224
	v_rcp_f32_e32 v225, v225
	v_rcp_f32_e32 v228, v228
	v_rcp_f32_e32 v229, v229
	s_nop 0
	v_pk_mul_f32 v[246:247], v[200:201], v[246:247]
	v_pk_mul_f32 v[248:249], v[202:203], v[248:249]
	v_pk_mul_f32 v[224:225], v[204:205], v[224:225]
	v_pk_mul_f32 v[228:229], v[206:207], v[228:229]
	v_pk_mul_f32 v[246:247], v[46:47], v[246:247]
	v_pk_mul_f32 v[248:249], v[48:49], v[248:249]
	v_pk_mul_f32 v[224:225], v[42:43], v[224:225]
	v_pk_mul_f32 v[228:229], v[44:45], v[228:229]
	v_cvt_pk_bf16_f32 v42, v246, v247
	v_add_u32_e32 v46, 0x90, v240
	v_mad_i64_i32 v[46:47], s[4:5], v46, s79, v[132:133]
	v_lshl_add_u64 v[46:47], v[46:47], 0, v[134:135]
	v_cvt_pk_bf16_f32 v43, v248, v249
	v_cvt_pk_bf16_f32 v44, v224, v225
	v_cvt_pk_bf16_f32 v45, v228, v229
	global_store_dwordx4 v[46:47], v[42:45], off
	s_nop 1
	v_pk_fma_f32 v[200:201], v[22:23], v[156:157], v[128:129]
	v_fmac_f32_dpp v200, v22, v148 row_shr:1 row_mask:0xf bank_mask:0xf
	v_fmac_f32_dpp v200, v38, v148 row_shl:15 row_mask:0xf bank_mask:0xf
	v_fmac_f32_dpp v200, v22, v152 row_shl:1 row_mask:0xf bank_mask:0xf
	v_fmac_f32_dpp v200, v14, v152 row_shr:15 row_mask:0xf bank_mask:0xf
	v_fmac_f32_dpp v201, v23, v149 row_shr:1 row_mask:0xf bank_mask:0xf
	v_fmac_f32_dpp v201, v39, v149 row_shl:15 row_mask:0xf bank_mask:0xf
	v_fmac_f32_dpp v201, v23, v153 row_shl:1 row_mask:0xf bank_mask:0xf
	v_fmac_f32_dpp v201, v15, v153 row_shr:15 row_mask:0xf bank_mask:0xf
	v_pk_fma_f32 v[202:203], v[24:25], v[158:159], v[130:131]
	v_fmac_f32_dpp v202, v24, v150 row_shr:1 row_mask:0xf bank_mask:0xf
	v_fmac_f32_dpp v202, v40, v150 row_shl:15 row_mask:0xf bank_mask:0xf
	v_fmac_f32_dpp v202, v24, v154 row_shl:1 row_mask:0xf bank_mask:0xf
	v_fmac_f32_dpp v202, v16, v154 row_shr:15 row_mask:0xf bank_mask:0xf
	v_fmac_f32_dpp v203, v25, v151 row_shr:1 row_mask:0xf bank_mask:0xf
	v_fmac_f32_dpp v203, v41, v151 row_shl:15 row_mask:0xf bank_mask:0xf
	v_fmac_f32_dpp v203, v25, v155 row_shl:1 row_mask:0xf bank_mask:0xf
	v_fmac_f32_dpp v203, v17, v155 row_shr:15 row_mask:0xf bank_mask:0xf
	v_pk_fma_f32 v[204:205], v[18:19], v[144:145], v[120:121]
	v_fmac_f32_dpp v204, v18, v136 row_shr:1 row_mask:0xf bank_mask:0xf
	v_fmac_f32_dpp v204, v34, v136 row_shl:15 row_mask:0xf bank_mask:0xf
	v_fmac_f32_dpp v204, v18, v140 row_shl:1 row_mask:0xf bank_mask:0xf
	v_fmac_f32_dpp v204, v10, v140 row_shr:15 row_mask:0xf bank_mask:0xf
	v_fmac_f32_dpp v205, v19, v137 row_shr:1 row_mask:0xf bank_mask:0xf
	v_fmac_f32_dpp v205, v35, v137 row_shl:15 row_mask:0xf bank_mask:0xf
	v_fmac_f32_dpp v205, v19, v141 row_shl:1 row_mask:0xf bank_mask:0xf
	v_fmac_f32_dpp v205, v11, v141 row_shr:15 row_mask:0xf bank_mask:0xf
	v_pk_fma_f32 v[206:207], v[20:21], v[146:147], v[122:123]
	v_fmac_f32_dpp v206, v20, v138 row_shr:1 row_mask:0xf bank_mask:0xf
	v_fmac_f32_dpp v206, v36, v138 row_shl:15 row_mask:0xf bank_mask:0xf
	v_fmac_f32_dpp v206, v20, v142 row_shl:1 row_mask:0xf bank_mask:0xf
	v_fmac_f32_dpp v206, v12, v142 row_shr:15 row_mask:0xf bank_mask:0xf
	v_fmac_f32_dpp v207, v21, v139 row_shr:1 row_mask:0xf bank_mask:0xf
	v_fmac_f32_dpp v207, v37, v139 row_shl:15 row_mask:0xf bank_mask:0xf
	v_fmac_f32_dpp v207, v21, v143 row_shl:1 row_mask:0xf bank_mask:0xf
	v_fmac_f32_dpp v207, v13, v143 row_shr:15 row_mask:0xf bank_mask:0xf
	v_exp_f32_e32 v246, v200
	v_exp_f32_e32 v247, v201
	v_exp_f32_e32 v248, v202
	v_exp_f32_e32 v249, v203
	v_exp_f32_e32 v224, v204
	v_exp_f32_e32 v225, v205
	v_exp_f32_e32 v228, v206
	v_exp_f32_e32 v229, v207
	v_pk_fma_f32 v[246:247], v[246:247], s[100:101], s[100:101]
	v_pk_fma_f32 v[248:249], v[248:249], s[100:101], s[100:101]
	v_pk_fma_f32 v[224:225], v[224:225], s[100:101], s[100:101]
	v_pk_fma_f32 v[228:229], v[228:229], s[100:101], s[100:101]
	v_rcp_f32_e32 v246, v246
	v_rcp_f32_e32 v247, v247
	v_rcp_f32_e32 v248, v248
	v_rcp_f32_e32 v249, v249
	v_rcp_f32_e32 v224, v224
	v_rcp_f32_e32 v225, v225
	v_rcp_f32_e32 v228, v228
	v_rcp_f32_e32 v229, v229
	s_nop 0
	v_pk_mul_f32 v[246:247], v[200:201], v[246:247]
	v_pk_mul_f32 v[248:249], v[202:203], v[248:249]
	v_pk_mul_f32 v[224:225], v[204:205], v[224:225]
	v_pk_mul_f32 v[228:229], v[206:207], v[228:229]
	v_pk_mul_f32 v[246:247], v[30:31], v[246:247]
	v_pk_mul_f32 v[248:249], v[32:33], v[248:249]
	v_pk_mul_f32 v[224:225], v[26:27], v[224:225]
	v_pk_mul_f32 v[228:229], v[28:29], v[228:229]
	v_cvt_pk_bf16_f32 v26, v246, v247
	v_add_u32_e32 v30, 0xa0, v240
	v_mad_i64_i32 v[30:31], s[4:5], v30, s79, v[132:133]
	v_lshl_add_u64 v[30:31], v[30:31], 0, v[134:135]
	v_cvt_pk_bf16_f32 v27, v248, v249
	v_cvt_pk_bf16_f32 v28, v224, v225
	v_cvt_pk_bf16_f32 v29, v228, v229
	global_store_dwordx4 v[30:31], v[26:29], off
	v_pk_fma_f32 v[206:207], v[12:13], v[146:147], v[122:123]
	v_pk_fma_f32 v[202:203], v[16:17], v[158:159], v[130:131]
	v_pk_fma_f32 v[200:201], v[14:15], v[156:157], v[128:129]
	s_nop 1
	v_fmac_f32_dpp v200, v14, v148 row_shr:1 row_mask:0xf bank_mask:0xf
	v_fmac_f32_dpp v200, v22, v148 row_shl:15 row_mask:0xf bank_mask:0xf
	v_fmac_f32_dpp v200, v14, v152 row_shl:1 row_mask:0xf bank_mask:0xf
	v_fmac_f32_dpp v200, v168, v152 row_shr:15 row_mask:0xf bank_mask:0xf
	v_fmac_f32_dpp v201, v15, v149 row_shr:1 row_mask:0xf bank_mask:0xf
	v_fmac_f32_dpp v201, v23, v149 row_shl:15 row_mask:0xf bank_mask:0xf
	v_fmac_f32_dpp v201, v15, v153 row_shl:1 row_mask:0xf bank_mask:0xf
	v_fmac_f32_dpp v201, v169, v153 row_shr:15 row_mask:0xf bank_mask:0xf
	v_fmac_f32_dpp v202, v16, v150 row_shr:1 row_mask:0xf bank_mask:0xf
	v_fmac_f32_dpp v202, v24, v150 row_shl:15 row_mask:0xf bank_mask:0xf
	v_fmac_f32_dpp v202, v16, v154 row_shl:1 row_mask:0xf bank_mask:0xf
	v_fmac_f32_dpp v202, v170, v154 row_shr:15 row_mask:0xf bank_mask:0xf
	v_pk_fma_f32 v[204:205], v[10:11], v[144:145], v[120:121]
	v_fmac_f32_dpp v204, v10, v136 row_shr:1 row_mask:0xf bank_mask:0xf
	v_fmac_f32_dpp v204, v18, v136 row_shl:15 row_mask:0xf bank_mask:0xf
	v_fmac_f32_dpp v204, v10, v140 row_shl:1 row_mask:0xf bank_mask:0xf
	v_fmac_f32_dpp v204, v164, v140 row_shr:15 row_mask:0xf bank_mask:0xf
	v_fmac_f32_dpp v205, v11, v137 row_shr:1 row_mask:0xf bank_mask:0xf
	v_fmac_f32_dpp v205, v19, v137 row_shl:15 row_mask:0xf bank_mask:0xf
	v_fmac_f32_dpp v205, v11, v141 row_shl:1 row_mask:0xf bank_mask:0xf
	v_fmac_f32_dpp v205, v165, v141 row_shr:15 row_mask:0xf bank_mask:0xf
	v_fmac_f32_dpp v206, v12, v138 row_shr:1 row_mask:0xf bank_mask:0xf
	v_fmac_f32_dpp v206, v20, v138 row_shl:15 row_mask:0xf bank_mask:0xf
	v_fmac_f32_dpp v206, v12, v142 row_shl:1 row_mask:0xf bank_mask:0xf
	v_fmac_f32_dpp v206, v166, v142 row_shr:15 row_mask:0xf bank_mask:0xf
	v_fmac_f32_dpp v207, v13, v139 row_shr:1 row_mask:0xf bank_mask:0xf
	v_fmac_f32_dpp v207, v21, v139 row_shl:15 row_mask:0xf bank_mask:0xf
	v_fmac_f32_dpp v207, v13, v143 row_shl:1 row_mask:0xf bank_mask:0xf
	v_fmac_f32_dpp v207, v167, v143 row_shr:15 row_mask:0xf bank_mask:0xf
	v_fmac_f32_dpp v203, v17, v151 row_shr:1 row_mask:0xf bank_mask:0xf
	v_fmac_f32_dpp v203, v25, v151 row_shl:15 row_mask:0xf bank_mask:0xf
	v_fmac_f32_dpp v203, v17, v155 row_shl:1 row_mask:0xf bank_mask:0xf
	v_fmac_f32_dpp v203, v171, v155 row_shr:15 row_mask:0xf bank_mask:0xf
	v_exp_f32_e32 v246, v200
	v_exp_f32_e32 v247, v201
	v_exp_f32_e32 v248, v202
	v_exp_f32_e32 v249, v203
	v_exp_f32_e32 v224, v204
	v_exp_f32_e32 v225, v205
	v_exp_f32_e32 v228, v206
	v_exp_f32_e32 v229, v207
	v_pk_fma_f32 v[246:247], v[246:247], s[100:101], s[100:101]
	v_pk_fma_f32 v[248:249], v[248:249], s[100:101], s[100:101]
	v_pk_fma_f32 v[224:225], v[224:225], s[100:101], s[100:101]
	v_pk_fma_f32 v[228:229], v[228:229], s[100:101], s[100:101]
	v_rcp_f32_e32 v246, v246
	v_rcp_f32_e32 v247, v247
	v_rcp_f32_e32 v248, v248
	v_rcp_f32_e32 v249, v249
	v_rcp_f32_e32 v224, v224
	v_rcp_f32_e32 v225, v225
	v_rcp_f32_e32 v228, v228
	v_rcp_f32_e32 v229, v229
	s_nop 0
	v_pk_mul_f32 v[246:247], v[200:201], v[246:247]
	v_pk_mul_f32 v[248:249], v[202:203], v[248:249]
	v_pk_mul_f32 v[224:225], v[204:205], v[224:225]
	v_pk_mul_f32 v[228:229], v[206:207], v[228:229]
	v_pk_mul_f32 v[246:247], v[6:7], v[246:247]
	v_pk_mul_f32 v[248:249], v[8:9], v[248:249]
	v_pk_mul_f32 v[224:225], v[2:3], v[224:225]
	v_pk_mul_f32 v[228:229], v[4:5], v[228:229]
	v_cvt_pk_bf16_f32 v2, v246, v247
	v_add_u32_e32 v6, 0xb0, v240
	v_mad_i64_i32 v[6:7], s[4:5], v6, s79, v[132:133]
	v_lshl_add_u64 v[6:7], v[6:7], 0, v[134:135]
	s_mov_b64 s[4:5], -1
	v_cvt_pk_bf16_f32 v3, v248, v249
	v_cvt_pk_bf16_f32 v4, v224, v225
	v_cvt_pk_bf16_f32 v5, v228, v229
	global_store_dwordx4 v[6:7], v[2:5], off
	s_cbranch_vccnz .LBB0_972
	s_and_b64 vcc, exec, s[46:47]
	s_cbranch_vccnz .LBB0_971
	s_barrier
	s_branch .LBB0_971
